# attention unit setup: Q block loaded linearly (coalesced) and transposed to the MFMA operand layout through wave-private LDS
# baseline (speedup 1.0000x reference)
.LBB0_1160:
	v_ashrrev_i32_e32 v0, 1, v144
	s_movk_i32 s4, 0xffe0
	v_bfe_u32 v132, v144, 5, 1
	v_bfi_b32 v133, s4, v0, v144
	v_lshlrev_b32_e32 v16, 4, v132
	v_mov_b32_e32 v17, v4
	v_lshrrev_b32_e32 v6, 6, v144
	v_and_b32_e32 v7, 63, v144
	s_movk_i32 s4, 0x1800
	v_lshlrev_b32_e32 v7, 4, v7
	v_mad_u32_u24 v6, v6, s4, v7
	global_load_dwordx4 v[96:99], v6, s[0:1]
	global_load_dwordx4 v[100:103], v6, s[0:1] offset:1024
	global_load_dwordx4 v[104:107], v6, s[0:1] offset:2048
	global_load_dwordx4 v[108:111], v6, s[0:1] offset:3072
	v_ashrrev_i32_e32 v145, 31, v144
	v_lshl_add_u64 v[0:1], v[144:145], 4, s[12:13]
	global_load_dwordx4 v[0:3], v[0:1], off
	v_add_u32_e32 v7, 0x1000, v6
	global_load_dwordx4 v[112:115], v7, s[0:1]
	global_load_dwordx4 v[116:119], v7, s[0:1] offset:1024
	v_add_u32_e32 v150, 0x10020, v6
	v_mad_u32_u24 v151, v133, s50, v16
	v_add_u32_e32 v151, 0x10020, v151
	v_mov_b32_e32 v6, v4
	v_mov_b32_e32 v7, v4
	v_lshlrev_b64 v[14:15], 3, v[144:145]
	v_mov_b32_e32 v5, v4
	s_movk_i32 s0, 0xff
	v_cmp_lt_i32_e64 s[0:1], s0, v144
	v_cmp_gt_i32_e64 s[4:5], s33, v144
	v_lshl_add_u64 v[8:9], v[14:15], 1, s[14:15]
	s_waitcnt vmcnt(2)
	v_mov_b64_e32 v[86:87], v[6:7]
	v_mov_b64_e32 v[84:85], v[4:5]
	v_mov_b64_e32 v[82:83], v[2:3]
	v_mov_b64_e32 v[80:81], v[0:1]
	s_and_saveexec_b64 s[22:23], s[4:5]
	s_cbranch_execz .LBB0_1162
	global_load_dwordx4 v[10:13], v[8:9], off
	v_mov_b64_e32 v[86:87], v[6:7]
	v_mov_b64_e32 v[84:85], v[4:5]
	v_mov_b64_e32 v[82:83], v[2:3]
	v_mov_b64_e32 v[80:81], v[0:1]
	s_waitcnt vmcnt(0)
	v_mov_b32_e32 v84, v10
	v_mov_b32_e32 v85, v11
	v_mov_b32_e32 v86, v12
	v_mov_b32_e32 v87, v13

.LBB0_1164:
	s_or_b64 exec, exec, s[22:23]
	global_load_dwordx4 v[124:127], v[12:13], off offset:128
	s_movk_i32 s16, 0xd0
	v_mul_lo_u32 v0, v17, s16
	v_add_u32_e32 v1, 32, v0
	v_lshrrev_b32_e32 v2, 2, v144
	v_add_u32_e32 v134, v1, v10
	s_movk_i32 s51, 0xd0
	v_mul_lo_u32 v0, v2, s16
	v_and_b32_e32 v135, 48, v18
	ds_write_b128 v134, v[80:83]
	s_and_saveexec_b64 s[22:23], s[0:1]
	s_xor_b64 s[0:1], exec, s[22:23]
	v_mul_lo_u32 v0, v2, s51
	v_and_b32_e32 v135, 48, v18
	s_andn2_saveexec_b64 s[0:1], s[0:1]
	v_add3_u32 v2, 32, v0, v135
	ds_write_b128 v2, v[84:87] offset:128
	s_or_b64 exec, exec, s[0:1]
	v_lshlrev_b32_e32 v3, 3, v144
	v_lshlrev_b32_e32 v5, 6, v17
	v_and_b32_e32 v3, 8, v3
	s_movk_i32 s0, 0x60
	v_sub_u32_e32 v1, v1, v5
	v_and_or_b32 v3, v18, s0, v3
	v_cmp_lt_i32_e32 vcc, v248, v242
	v_and_b32_e32 v2, 31, v144
	v_add_u32_e32 v136, v1, v3
	v_cndmask_b32_e32 v1, v241, v248, vcc
	v_mad_u32_u24 v18, v2, s51, 32
	v_lshlrev_b32_e32 v146, 2, v1
	v_lshlrev_b32_e32 v1, 6, v2
	v_add_u32_e32 v147, 32, v0
	v_and_b32_e32 v0, 7, v144
	v_sub_u32_e32 v19, v18, v1
	v_lshlrev_b32_e32 v0, 4, v0
	v_mov_b32_e32 v1, v4
	v_lshlrev_b32_e32 v2, 1, v17
	v_mad_i64_i32 v[0:1], s[0:1], v2, s35, v[0:1]
	v_lshl_add_u64 v[0:1], s[20:21], 0, v[0:1]
	v_mov_b32_e32 v14, v4
	v_mov_b32_e32 v15, v4
	v_lshlrev_b64 v[128:129], 4, v[144:145]
	v_lshl_add_u64 v[130:131], v[0:1], 0, s[96:97]
	v_mov_b32_e32 v0, v4
	v_mov_b32_e32 v1, v4
	v_mov_b32_e32 v2, v4
	v_mov_b32_e32 v3, v4
	v_mov_b32_e32 v5, v4
	v_mov_b32_e32 v6, v4
	v_mov_b32_e32 v7, v4
	v_mov_b32_e32 v8, v4
	v_mov_b32_e32 v9, v4
	v_mov_b32_e32 v10, v4
	v_mov_b32_e32 v11, v4
	v_mov_b32_e32 v12, v4
	v_mov_b32_e32 v13, v4
	v_add_u32_e32 v144, v18, v16
	v_add_u32_e32 v145, v19, v16
	v_mov_b64_e32 v[30:31], v[14:15]
	v_mov_b64_e32 v[46:47], v[14:15]
	s_lshr_b32 s16, s35, 6
	v_add_u32_e32 v137, 0x3000, v136
	v_mov_b32_e32 v182, 0x80000000
	v_mov_b32_e32 v183, v182
	v_mov_b32_e32 v184, v182
	v_mov_b32_e32 v185, v182
	v_mov_b32_e32 v186, v182
	v_mov_b32_e32 v187, v182
	v_mov_b32_e32 v188, v182
	v_mov_b32_e32 v189, v182
	v_mov_b32_e32 v190, v182
	v_mov_b32_e32 v191, v182
	v_mov_b32_e32 v192, v182
	v_mov_b32_e32 v193, v182
	v_mov_b32_e32 v194, v182
	v_mov_b32_e32 v195, v182
	v_mov_b32_e32 v196, v182
	v_mov_b32_e32 v197, v182
	v_mov_b32_e32 v148, 0
	s_mov_b32 s22, 3
	v_mov_b64_e32 v[28:29], v[12:13]
	v_mov_b64_e32 v[26:27], v[10:11]
	v_mov_b64_e32 v[24:25], v[8:9]
	v_mov_b64_e32 v[22:23], v[6:7]
	v_mov_b64_e32 v[20:21], v[4:5]
	v_mov_b64_e32 v[18:19], v[2:3]
	v_mov_b64_e32 v[16:17], v[0:1]
	v_mov_b64_e32 v[44:45], v[12:13]
	v_mov_b64_e32 v[42:43], v[10:11]
	v_mov_b64_e32 v[40:41], v[8:9]
	v_mov_b64_e32 v[38:39], v[6:7]
	v_mov_b64_e32 v[36:37], v[4:5]
	v_mov_b64_e32 v[34:35], v[2:3]
	v_mov_b64_e32 v[32:33], v[0:1]
	v_mov_b32_e32 v0, 0
	s_waitcnt vmcnt(1)
	s_waitcnt lgkmcnt(0)
	ds_write_b128 v150, v[96:99]
	ds_write_b128 v150, v[100:103] offset:1024
	ds_write_b128 v150, v[104:107] offset:2048
	ds_write_b128 v150, v[108:111] offset:3072
	ds_write_b128 v150, v[112:115] offset:4096
	ds_write_b128 v150, v[116:119] offset:5120
	ds_read_b128 v[96:99], v151
	ds_read_b128 v[100:103], v151 offset:32
	ds_read_b128 v[104:107], v151 offset:64
	ds_read_b128 v[108:111], v151 offset:96
	ds_read_b128 v[112:115], v151 offset:128
	ds_read_b128 v[116:119], v151 offset:160
	ds_write2_b64 v137, v[120:121], v[122:123] offset0:128 offset1:130
	s_waitcnt lgkmcnt(0)
	s_barrier
	s_branch .LBB0_1171
